# grid barrier: XCD leaders poll the cross-XCD arrival counter (>= target) instead of the separate generation word
# baseline (speedup 1.0000x reference)
.LBB0_245:
	s_or_b64 exec, exec, s[12:13]
	v_cvt_f32_u32_e32 v3, v0
	s_waitcnt vmcnt(0)
	v_readfirstlane_b32 s4, v2
	v_sub_u32_e32 v2, 0, v0
	v_readlane_b32 s6, v249, 3
	v_rcp_iflag_f32_e32 v3, v3
	v_add_u32_e32 v1, s4, v1
	v_add_u32_e32 v4, 1, v1
	v_readlane_b32 s7, v249, 4
	v_mul_f32_e32 v3, 0x4f7ffffe, v3
	v_cvt_u32_f32_e32 v3, v3
	s_mov_b64 s[12:13], -1
	v_mul_lo_u32 v2, v2, v3
	v_mul_hi_u32 v2, v3, v2
	v_add_u32_e32 v2, v3, v2
	v_mul_hi_u32 v2, v1, v2
	v_mul_lo_u32 v3, v2, v0
	v_sub_u32_e32 v1, v1, v3
	v_add_u32_e32 v5, 1, v2
	v_sub_u32_e32 v3, v1, v0
	v_cmp_ge_u32_e32 vcc, v1, v0
	s_nop 1
	v_cndmask_b32_e32 v2, v2, v5, vcc
	v_cndmask_b32_e32 v1, v1, v3, vcc
	v_add_u32_e32 v3, 1, v2
	v_cmp_ge_u32_e32 vcc, v1, v0
	s_nop 1
	v_cndmask_b32_e32 v2, v2, v3, vcc
	v_mul_lo_u32 v1, v0, v2
	v_add_u32_e32 v0, v1, v0
	v_mov_b32_e32 v233, v0
	v_cmp_ne_u32_e32 vcc, v4, v0
	v_mov_b64_e32 v[0:1], s[6:7]
	s_and_saveexec_b64 s[6:7], vcc
	s_cbranch_execz .LBB0_257
	v_readlane_b32 s10, v249, 3
	v_readlane_b32 s11, v249, 4
	s_mov_b64 s[38:39], 0
	s_nop 3
	global_load_dword v0, v97, s[10:11] offset:-256 sc1
	s_waitcnt vmcnt(0)
	v_cmp_lt_u32_e32 vcc, v0, v233
	s_and_saveexec_b64 s[12:13], vcc
	s_cbranch_execz .LBB0_256
	s_mov_b32 s4, 1
	s_branch .LBB0_249

.LBB0_251:
	v_readlane_b32 s10, v249, 3
	v_readlane_b32 s11, v249, 4
	s_add_i32 s4, s4, 1
	s_mov_b64 s[44:45], -1
	s_nop 2
	global_load_dword v0, v97, s[10:11] offset:-256 sc1
	s_waitcnt vmcnt(0)
	v_cmp_ge_u32_e32 vcc, v0, v233
	s_orn2_b64 s[42:43], vcc, exec
	s_branch .LBB0_248

.LBB0_373:
	s_or_b64 exec, exec, s[6:7]
	s_waitcnt vmcnt(0)
	v_readfirstlane_b32 s2, v2
	v_cvt_f32_u32_e32 v2, v0
	v_sub_u32_e32 v3, 0, v0
	v_add_u32_e32 v1, s2, v1
	v_readlane_b32 s2, v249, 3
	v_rcp_iflag_f32_e32 v2, v2
	v_readlane_b32 s3, v249, 4
	s_mov_b64 s[6:7], -1
	v_mul_f32_e32 v2, 0x4f7ffffe, v2
	v_cvt_u32_f32_e32 v2, v2
	v_mul_lo_u32 v3, v3, v2
	v_mul_hi_u32 v3, v2, v3
	v_add_u32_e32 v2, v2, v3
	v_mul_hi_u32 v2, v1, v2
	v_mul_lo_u32 v3, v2, v0
	v_sub_u32_e32 v3, v1, v3
	v_cmp_ge_u32_e32 vcc, v3, v0
	v_add_u32_e32 v4, 1, v2
	v_add_u32_e32 v1, 1, v1
	v_cndmask_b32_e32 v2, v2, v4, vcc
	v_sub_u32_e32 v4, v3, v0
	v_cndmask_b32_e32 v3, v3, v4, vcc
	v_cmp_ge_u32_e32 vcc, v3, v0
	v_add_u32_e32 v3, 1, v2
	s_nop 0
	v_cndmask_b32_e32 v2, v2, v3, vcc
	v_mul_lo_u32 v3, v0, v2
	v_add_u32_e32 v0, v3, v0
	v_mov_b32_e32 v233, v0
	v_cmp_ne_u32_e32 vcc, v1, v0
	v_mov_b64_e32 v[0:1], s[2:3]
	s_and_saveexec_b64 s[2:3], vcc
	s_cbranch_execz .LBB0_385
	v_readlane_b32 s6, v249, 3
	v_readlane_b32 s7, v249, 4
	s_mov_b64 s[12:13], 0
	s_nop 3
	global_load_dword v0, v97, s[6:7] offset:-256 sc1
	s_waitcnt vmcnt(0)
	v_cmp_lt_u32_e32 vcc, v0, v233
	s_and_saveexec_b64 s[6:7], vcc
	s_cbranch_execz .LBB0_384
	s_mov_b32 s4, 1
	s_branch .LBB0_377

.LBB0_379:
	v_readlane_b32 s10, v249, 3
	v_readlane_b32 s11, v249, 4
	s_add_i32 s4, s4, 1
	s_mov_b64 s[42:43], -1
	s_nop 2
	global_load_dword v0, v97, s[10:11] offset:-256 sc1
	s_waitcnt vmcnt(0)
	v_cmp_ge_u32_e32 vcc, v0, v233
	s_orn2_b64 s[40:41], vcc, exec
	s_branch .LBB0_376

.LBB0_424:
	s_or_b64 exec, exec, s[12:13]
	s_waitcnt vmcnt(0)
	v_readfirstlane_b32 s4, v2
	v_cvt_f32_u32_e32 v2, v0
	v_sub_u32_e32 v3, 0, v0
	v_add_u32_e32 v1, s4, v1
	v_readlane_b32 s6, v249, 3
	v_rcp_iflag_f32_e32 v2, v2
	v_readlane_b32 s7, v249, 4
	s_mov_b64 s[12:13], -1
	v_mul_f32_e32 v2, 0x4f7ffffe, v2
	v_cvt_u32_f32_e32 v2, v2
	v_mul_lo_u32 v3, v3, v2
	v_mul_hi_u32 v3, v2, v3
	v_add_u32_e32 v2, v2, v3
	v_mul_hi_u32 v2, v1, v2
	v_mul_lo_u32 v3, v2, v0
	v_sub_u32_e32 v3, v1, v3
	v_cmp_ge_u32_e32 vcc, v3, v0
	v_add_u32_e32 v4, 1, v2
	v_add_u32_e32 v1, 1, v1
	v_cndmask_b32_e32 v2, v2, v4, vcc
	v_sub_u32_e32 v4, v3, v0
	v_cndmask_b32_e32 v3, v3, v4, vcc
	v_cmp_ge_u32_e32 vcc, v3, v0
	v_add_u32_e32 v3, 1, v2
	s_nop 0
	v_cndmask_b32_e32 v2, v2, v3, vcc
	v_mul_lo_u32 v3, v0, v2
	v_add_u32_e32 v0, v3, v0
	v_mov_b32_e32 v233, v0
	v_cmp_ne_u32_e32 vcc, v1, v0
	v_mov_b64_e32 v[0:1], s[6:7]
	s_and_saveexec_b64 s[6:7], vcc
	s_cbranch_execz .LBB0_436
	v_readlane_b32 s8, v249, 3
	v_readlane_b32 s9, v249, 4
	s_mov_b64 s[38:39], 0
	s_nop 3
	global_load_dword v0, v97, s[8:9] offset:-256 sc1
	s_waitcnt vmcnt(0)
	v_cmp_lt_u32_e32 vcc, v0, v233
	s_and_saveexec_b64 s[12:13], vcc
	s_cbranch_execz .LBB0_435
	s_mov_b32 s4, 1
	s_branch .LBB0_428

.LBB0_430:
	v_readlane_b32 s8, v249, 3
	v_readlane_b32 s9, v249, 4
	s_add_i32 s4, s4, 1
	s_mov_b64 s[44:45], -1
	s_nop 2
	global_load_dword v0, v97, s[8:9] offset:-256 sc1
	s_waitcnt vmcnt(0)
	v_cmp_ge_u32_e32 vcc, v0, v233
	s_orn2_b64 s[42:43], vcc, exec
	s_branch .LBB0_427

.LBB0_679:
	v_readlane_b32 s8, v249, 3
	v_readlane_b32 s9, v249, 4
	s_add_i32 s4, s4, 1
	s_mov_b64 s[42:43], -1
	s_nop 2
	global_load_dword v0, v97, s[8:9] offset:-256 sc1
	s_waitcnt vmcnt(0)
	v_cmp_ge_u32_e32 vcc, v0, v233
	s_orn2_b64 s[40:41], vcc, exec
	s_branch .LBB0_676

.LBB0_1279:
	s_or_b64 exec, exec, s[12:13]
	s_waitcnt vmcnt(0)
	v_readfirstlane_b32 s6, v2
	v_cvt_f32_u32_e32 v2, v0
	v_sub_u32_e32 v3, 0, v0
	v_add_u32_e32 v1, s6, v1
	v_readlane_b32 s6, v249, 3
	v_rcp_iflag_f32_e32 v2, v2
	v_readlane_b32 s7, v249, 4
	s_mov_b64 s[12:13], -1
	v_mul_f32_e32 v2, 0x4f7ffffe, v2
	v_cvt_u32_f32_e32 v2, v2
	v_mul_lo_u32 v3, v3, v2
	v_mul_hi_u32 v3, v2, v3
	v_add_u32_e32 v2, v2, v3
	v_mul_hi_u32 v2, v1, v2
	v_mul_lo_u32 v3, v2, v0
	v_sub_u32_e32 v3, v1, v3
	v_cmp_ge_u32_e32 vcc, v3, v0
	v_add_u32_e32 v4, 1, v2
	v_add_u32_e32 v1, 1, v1
	v_cndmask_b32_e32 v2, v2, v4, vcc
	v_sub_u32_e32 v4, v3, v0
	v_cndmask_b32_e32 v3, v3, v4, vcc
	v_cmp_ge_u32_e32 vcc, v3, v0
	v_add_u32_e32 v3, 1, v2
	s_nop 0
	v_cndmask_b32_e32 v2, v2, v3, vcc
	v_mul_lo_u32 v3, v0, v2
	v_add_u32_e32 v0, v3, v0
	v_mov_b32_e32 v233, v0
	v_cmp_ne_u32_e32 vcc, v1, v0
	v_mov_b64_e32 v[0:1], s[6:7]
	s_and_saveexec_b64 s[6:7], vcc
	s_cbranch_execz .LBB0_1291
	v_readlane_b32 s8, v249, 3
	v_readlane_b32 s9, v249, 4
	s_mov_b64 s[38:39], 0
	s_nop 3
	global_load_dword v0, v97, s[8:9] offset:-256 sc1
	s_waitcnt vmcnt(0)
	v_cmp_lt_u32_e32 vcc, v0, v233
	s_and_saveexec_b64 s[12:13], vcc
	s_cbranch_execz .LBB0_1290
	s_mov_b32 s50, 1
	s_branch .LBB0_1283

.LBB0_1285:
	v_readlane_b32 s8, v249, 3
	v_readlane_b32 s9, v249, 4
	s_add_i32 s50, s50, 1
	s_mov_b64 s[46:47], -1
	s_nop 2
	global_load_dword v0, v97, s[8:9] offset:-256 sc1
	s_waitcnt vmcnt(0)
	v_cmp_ge_u32_e32 vcc, v0, v233
	s_orn2_b64 s[44:45], vcc, exec
	s_branch .LBB0_1282

.LBB0_1330:
	s_or_b64 exec, exec, s[38:39]
	s_waitcnt vmcnt(0)
	v_readfirstlane_b32 s12, v2
	v_cvt_f32_u32_e32 v2, v0
	v_sub_u32_e32 v3, 0, v0
	v_add_u32_e32 v1, s12, v1
	v_readlane_b32 s8, v249, 3
	v_rcp_iflag_f32_e32 v2, v2
	v_readlane_b32 s9, v249, 4
	s_mov_b64 s[38:39], -1
	v_mul_f32_e32 v2, 0x4f7ffffe, v2
	v_cvt_u32_f32_e32 v2, v2
	v_mul_lo_u32 v3, v3, v2
	v_mul_hi_u32 v3, v2, v3
	v_add_u32_e32 v2, v2, v3
	v_mul_hi_u32 v2, v1, v2
	v_mul_lo_u32 v3, v2, v0
	v_sub_u32_e32 v3, v1, v3
	v_cmp_ge_u32_e32 vcc, v3, v0
	v_add_u32_e32 v4, 1, v2
	v_add_u32_e32 v1, 1, v1
	v_cndmask_b32_e32 v2, v2, v4, vcc
	v_sub_u32_e32 v4, v3, v0
	v_cndmask_b32_e32 v3, v3, v4, vcc
	v_cmp_ge_u32_e32 vcc, v3, v0
	v_add_u32_e32 v3, 1, v2
	s_nop 0
	v_cndmask_b32_e32 v2, v2, v3, vcc
	v_mul_lo_u32 v3, v0, v2
	v_add_u32_e32 v0, v3, v0
	v_mov_b32_e32 v233, v0
	v_cmp_ne_u32_e32 vcc, v1, v0
	v_mov_b64_e32 v[0:1], s[8:9]
	s_and_saveexec_b64 s[12:13], vcc
	s_cbranch_execz .LBB0_1342
	v_readlane_b32 s8, v249, 3
	v_readlane_b32 s9, v249, 4
	s_mov_b64 s[40:41], 0
	s_nop 3
	global_load_dword v0, v97, s[8:9] offset:-256 sc1
	s_waitcnt vmcnt(0)
	v_cmp_lt_u32_e32 vcc, v0, v233
	s_and_saveexec_b64 s[38:39], vcc
	s_cbranch_execz .LBB0_1341
	s_mov_b32 s52, 1
	s_branch .LBB0_1334

.LBB0_1336:
	v_readlane_b32 s8, v249, 3
	v_readlane_b32 s9, v249, 4
	s_add_i32 s52, s52, 1
	s_mov_b64 s[48:49], -1
	s_nop 2
	global_load_dword v0, v97, s[8:9] offset:-256 sc1
	s_waitcnt vmcnt(0)
	v_cmp_ge_u32_e32 vcc, v0, v233
	s_orn2_b64 s[46:47], vcc, exec
	s_branch .LBB0_1333
